# attention QK section: double-buffered LDS fragment reads, next-tile global loads moved behind QK
# speedup vs baseline: 1.0035x; 1.0035x over previous
; #define LAS __attribute__((address_space(3)))
; __device__ __forceinline__ f32x4 mma16(bf16x8 a, bf16x8 b, f32x4 c) { return __builtin_amdgcn_mfma_f32_16x16x32_bf16(a, b, c, 0, 0, 0); }
; __device__ __forceinline__ void attn_phase(LAS unsigned char* lds, const bf16_t* proj, bf16_t* oa, const float* lamp, const float* subg, const float* relb, const float* qg, int wg, int tid) {
;     ...
;         for (int kt = 0; kt < nkt; ++kt) {
;             const int cur = kt & 1, k0 = kt * 32; const bool more = kt + 1 < nkt;
;             u32x4 kr[2], vr[2];
;             if (more) {
; #pragma unroll
;                 for (int i = 0; i < 2; ++i) { const int id = tid + 512 * i, s = id >> 9, row = (id >> 4) & 31, ch = id & 15; kr[i] = *(const u32x4*)(ksrc + (size_t)(k0 + 32 + row) * DIFF_IN + s * 128 + ch * 8); }
; #pragma unroll
;                 for (int i = 0; i < 2; ++i) { const int id = tid + 512 * i, row = id >> 5, ch = id & 31; vr[i] = *(const u32x4*)(vsrc + (size_t)(k0 + 32 + row) * DIFF_IN + ch * 8); }
;             }
;             if (k0 <= qw0 + 15) {
;                 const LAS bf16_t* Kc = Kb + cur * KB_BUF; const LAS bf16_t* Vc = Vb + cur * VB_BUF;
;                 const bool far = (qw0 - (k0 + 31)) >= 128;
;                 f32x4 st[2][2];
;                 int qoff = (fr * KP + 8 * fq); asm volatile("" : "+v"(qoff));
; #pragma unroll
;                 for (int s = 0; s < 2; ++s) { const float ini = far ? (s ? c31b : c31a) : 0.f;
;                     st[s][0] = (f32x4){ini, ini, ini, ini}; st[s][1] = st[s][0];
; #pragma unroll
;                     for (int ks = 0; ks < 4; ++ks) { const bf16x8 qfr = *(const LAS bf16x8*)(Qw + s * 16 * KP + qoff + 32 * ks);
; #pragma unroll
;                         for (int T = 0; T < 2; ++T) st[s][T] = mma16(frag_rowk(Kc + s * 32 * KP, KP, 16 * T, 32 * ks, fr, fq), qfr, st[s][T]); } }
.LBB0_595:
	s_cmp_lt_u32 s33, s34
	s_cselect_b64 s[20:21], -1, 0
	s_cmp_ge_u32 s33, s34
	s_cselect_b64 s[0:1], -1, 0
	s_add_i32 s30, s33, -1
	s_and_b32 s46, s30, 1
	s_cmp_gt_i32 s37, s35
	s_cbranch_scc0 .Lat_compute
	s_andn2_b64 vcc, exec, s[20:21]
	s_cbranch_vccnz .LBB0_594
	v_lshl_add_u64 v[2:3], v[212:213], 0, s[72:73]
	v_lshl_add_u64 v[6:7], v[210:211], 0, s[72:73]
	v_lshl_add_u64 v[10:11], v[214:215], 0, s[72:73]
	v_lshl_add_u64 v[14:15], v[216:217], 0, s[72:73]
	global_load_dwordx4 v[2:5], v[2:3], off
	s_nop 0
	global_load_dwordx4 v[6:9], v[6:7], off
	s_nop 0
	global_load_dwordx4 v[10:13], v[10:11], off
	s_nop 0
	global_load_dwordx4 v[14:17], v[14:15], off
	s_branch .LBB0_634
.Lat_compute:
	v_lshl_add_u32 v0, v236, 1, s44
	s_mul_i32 s30, s46, 0x4800
	v_add_u32_e32 v224, s30, v245
	ds_read_b128 v[2:5], v0
	ds_read_b128 v[6:9], v224
	ds_read_b128 v[10:13], v224 offset:4608
	ds_read_b128 v[14:17], v0 offset:64
	ds_read_b128 v[162:165], v224 offset:64
	ds_read_b128 v[220:223], v224 offset:4672
	s_cmpk_gt_i32 s36, 0x7f
	s_cselect_b64 vcc, -1, 0
	v_cndmask_b32_e32 v228, 0, v243, vcc
	v_mov_b32_e32 v229, v228
	v_mov_b32_e32 v230, v228
	v_mov_b32_e32 v231, v228
	s_waitcnt lgkmcnt(3)
	s_nop 1
	v_mfma_f32_16x16x32_bf16 v[146:149], v[6:9], v[2:5], v[228:231]
	v_mfma_f32_16x16x32_bf16 v[150:153], v[10:13], v[2:5], v[228:231]
	ds_read_b128 v[2:5], v0 offset:128
	ds_read_b128 v[6:9], v224 offset:128
	ds_read_b128 v[10:13], v224 offset:4736
	s_waitcnt lgkmcnt(3)
	v_mfma_f32_16x16x32_bf16 v[146:149], v[162:165], v[14:17], v[146:149]
	v_mfma_f32_16x16x32_bf16 v[150:153], v[220:223], v[14:17], v[150:153]
	ds_read_b128 v[14:17], v0 offset:192
	ds_read_b128 v[162:165], v224 offset:192
	ds_read_b128 v[220:223], v224 offset:4800
	s_waitcnt lgkmcnt(3)
	v_mfma_f32_16x16x32_bf16 v[146:149], v[6:9], v[2:5], v[146:149]
	v_mfma_f32_16x16x32_bf16 v[150:153], v[10:13], v[2:5], v[150:153]
	ds_read_b128 v[2:5], v0 offset:4608
	ds_read_b128 v[6:9], v224 offset:9216
	ds_read_b128 v[10:13], v224 offset:13824
	s_waitcnt lgkmcnt(3)
	v_mfma_f32_16x16x32_bf16 v[146:149], v[162:165], v[14:17], v[146:149]
	v_mfma_f32_16x16x32_bf16 v[150:153], v[220:223], v[14:17], v[150:153]
	ds_read_b128 v[14:17], v0 offset:4672
	ds_read_b128 v[162:165], v224 offset:9280
	ds_read_b128 v[220:223], v224 offset:13888
	v_cndmask_b32_e32 v228, 0, v244, vcc
	v_mov_b32_e32 v229, v228
	v_mov_b32_e32 v230, v228
	v_mov_b32_e32 v231, v228
	s_waitcnt lgkmcnt(3)
	s_nop 1
	v_mfma_f32_16x16x32_bf16 v[158:161], v[6:9], v[2:5], v[228:231]
	v_mfma_f32_16x16x32_bf16 v[154:157], v[10:13], v[2:5], v[228:231]
	ds_read_b128 v[2:5], v0 offset:4736
	ds_read_b128 v[6:9], v224 offset:9344
	ds_read_b128 v[10:13], v224 offset:13952
	s_waitcnt lgkmcnt(3)
	v_mfma_f32_16x16x32_bf16 v[158:161], v[162:165], v[14:17], v[158:161]
	v_mfma_f32_16x16x32_bf16 v[154:157], v[220:223], v[14:17], v[154:157]
	ds_read_b128 v[14:17], v0 offset:4800
	ds_read_b128 v[162:165], v224 offset:9408
	ds_read_b128 v[220:223], v224 offset:14016
	s_waitcnt lgkmcnt(3)
	v_mfma_f32_16x16x32_bf16 v[158:161], v[6:9], v[2:5], v[158:161]
	v_mfma_f32_16x16x32_bf16 v[154:157], v[10:13], v[2:5], v[154:157]
	s_waitcnt lgkmcnt(0)
	v_mfma_f32_16x16x32_bf16 v[158:161], v[162:165], v[14:17], v[158:161]
	v_mfma_f32_16x16x32_bf16 v[154:157], v[220:223], v[14:17], v[154:157]
	s_and_b64 s[98:99], s[20:21], exec
	s_cbranch_scc0 .Lat_noload
	v_lshl_add_u64 v[2:3], v[212:213], 0, s[72:73]
	v_lshl_add_u64 v[6:7], v[210:211], 0, s[72:73]
	v_lshl_add_u64 v[10:11], v[214:215], 0, s[72:73]
	v_lshl_add_u64 v[14:15], v[216:217], 0, s[72:73]
	global_load_dwordx4 v[2:5], v[2:3], off
	s_nop 0
	global_load_dwordx4 v[6:9], v[6:7], off
	s_nop 0
	global_load_dwordx4 v[10:13], v[10:11], off
	s_nop 0
	global_load_dwordx4 v[14:17], v[14:15], off
.Lat_noload:
	s_and_b64 vcc, exec, vcc
	s_cbranch_vccnz .LBB0_633
	v_add_u32_e32 v0, s36, v247
	v_mov_b64_e32 v[164:165], v[148:149]
	v_add_u32_e32 v220, 31, v0
	v_mov_b64_e32 v[162:163], v[146:147]
	v_cmp_lt_i32_e32 vcc, -1, v220
	v_mov_b32_e32 v162, s78
	s_and_saveexec_b64 s[42:43], vcc
	s_xor_b64 s[42:43], exec, s[42:43]
	s_cbranch_execz .LBB0_602
	v_min_u32_e32 v162, 0x80, v220
	v_lshl_add_u32 v162, v162, 2, 0
	v_add_u32_e32 v162, 0x11800, v162
	ds_read2_b32 v[162:163], v162 offset1:132
	s_waitcnt lgkmcnt(0)
	v_add_f32_e32 v146, v146, v162
	v_add_f32_e32 v158, v158, v163
	v_mov_b64_e32 v[164:165], v[148:149]
	v_mov_b64_e32 v[162:163], v[146:147]

; __global__ void __launch_bounds__(NTHR) mega_fwd(Args a) {
	.amdhsa_kernel _Z8mega_fwd4Args
		.amdhsa_group_segment_fixed_size 0
		.amdhsa_private_segment_fixed_size 0
		.amdhsa_kernarg_size 424
		.amdhsa_user_sgpr_count 2
		.amdhsa_user_sgpr_dispatch_ptr 0
		.amdhsa_user_sgpr_queue_ptr 0
		.amdhsa_user_sgpr_kernarg_segment_ptr 1
		.amdhsa_user_sgpr_dispatch_id 0
		.amdhsa_user_sgpr_kernarg_preload_length 0
		.amdhsa_user_sgpr_kernarg_preload_offset 0
		.amdhsa_user_sgpr_private_segment_size 0
		.amdhsa_uses_dynamic_stack 0
		.amdhsa_enable_private_segment 0
		.amdhsa_system_sgpr_workgroup_id_x 1
		.amdhsa_system_sgpr_workgroup_id_y 0
		.amdhsa_system_sgpr_workgroup_id_z 0
		.amdhsa_system_sgpr_workgroup_info 0
		.amdhsa_system_vgpr_workitem_id 2
		.amdhsa_next_free_vgpr 256
		.amdhsa_next_free_sgpr 102
		.amdhsa_accum_offset 256
		.amdhsa_reserve_vcc 1
		.amdhsa_float_round_mode_32 0
		.amdhsa_float_round_mode_16_64 0
		.amdhsa_float_denorm_mode_32 3
		.amdhsa_float_denorm_mode_16_64 3
		.amdhsa_dx10_clamp 1
		.amdhsa_ieee_mode 1
		.amdhsa_fp16_overflow 0
		.amdhsa_tg_split 0
		.amdhsa_exception_fp_ieee_invalid_op 0
		.amdhsa_exception_fp_denorm_src 0
		.amdhsa_exception_fp_ieee_div_zero 0
		.amdhsa_exception_fp_ieee_overflow 0
		.amdhsa_exception_fp_ieee_underflow 0
		.amdhsa_exception_fp_ieee_inexact 0
		.amdhsa_exception_int_div_zero 0
	.end_amdhsa_kernel

; __global__ void __launch_bounds__(NTHR) mega_fwd(Args a) {
amdhsa.kernels:
  - .agpr_count:     0
    .args:
      - .offset:         0
        .size:           168
        .value_kind:     by_value
      - .offset:         168
        .size:           4
        .value_kind:     hidden_block_count_x
      - .offset:         172
        .size:           4
        .value_kind:     hidden_block_count_y
      - .offset:         176
        .size:           4
        .value_kind:     hidden_block_count_z
      - .offset:         180
        .size:           2
        .value_kind:     hidden_group_size_x
      - .offset:         182
        .size:           2
        .value_kind:     hidden_group_size_y
      - .offset:         184
        .size:           2
        .value_kind:     hidden_group_size_z
      - .offset:         186
        .size:           2
        .value_kind:     hidden_remainder_x
      - .offset:         188
        .size:           2
        .value_kind:     hidden_remainder_y
      - .offset:         190
        .size:           2
        .value_kind:     hidden_remainder_z
      - .offset:         208
        .size:           8
        .value_kind:     hidden_global_offset_x
      - .offset:         216
        .size:           8
        .value_kind:     hidden_global_offset_y
      - .offset:         224
        .size:           8
        .value_kind:     hidden_global_offset_z
      - .offset:         232
        .size:           2
        .value_kind:     hidden_grid_dims
      - .offset:         256
        .size:           8
        .value_kind:     hidden_multigrid_sync_arg
      - .offset:         288
        .size:           4
        .value_kind:     hidden_dynamic_lds_size
    .group_segment_fixed_size: 0
    .kernarg_segment_align: 8
    .kernarg_segment_size: 424
    .language:       OpenCL C
    .language_version:
      - 2
      - 0
    .max_flat_workgroup_size: 512
    .name:           _Z8mega_fwd4Args
    .private_segment_fixed_size: 0
    .sgpr_count:     108
    .sgpr_spill_count: 248
    .symbol:         _Z8mega_fwd4Args.kd
    .uniform_work_group_size: 1
    .uses_dynamic_stack: false
    .vgpr_count:     256
    .vgpr_spill_count: 0
    .wavefront_size: 64
